# SEL radix-select: per-pass 64-lane suffix scan via DPP row_shr/row_bcast + readlane total instead of 6 ds_bpermute steps (exact integer)
# speedup vs baseline: 1.0168x; 1.0035x over previous
; DI void select_item(const P& p, int b, int quad4, int bid, char* smem, const SelPre& pre) {
;     ...
;       const uint4 h4 = *(const uint4*)(hist + 4 * lane);
;       const unsigned sum = h4.x + h4.y + h4.z + h4.w;
;       unsigned incl = sum;
; #pragma unroll
;       for (int off = 1; off < 64; off <<= 1) { const unsigned v = __shfl_down(incl, off); if (lane + off < 64) incl += v; }
;       unsigned above = incl - sum;
;       const bool found = above < need && need <= incl;
.LBB0_469:
	s_or_b64 exec, exec, s[6:7]
	ds_read_b128 v[0:3], v23
	s_xor_b64 s[6:7], s[20:21], -1
	s_waitcnt lgkmcnt(0)
	v_add_u32_e32 v18, v1, v0
	v_add3_u32 v18, v18, v2, v3
	v_mov_b32_e32 v25, v18
	s_nop 1
	v_add_u32_dpp v25, v25, v25 row_shr:1 row_mask:0xf bank_mask:0xf bound_ctrl:0
	s_nop 1
	v_add_u32_dpp v25, v25, v25 row_shr:2 row_mask:0xf bank_mask:0xf bound_ctrl:0
	s_nop 1
	v_add_u32_dpp v25, v25, v25 row_shr:4 row_mask:0xf bank_mask:0xf bound_ctrl:0
	s_nop 1
	v_add_u32_dpp v25, v25, v25 row_shr:8 row_mask:0xf bank_mask:0xf bound_ctrl:0
	s_nop 1
	v_add_u32_dpp v25, v25, v25 row_bcast:15 row_mask:0xa bank_mask:0xf
	s_nop 1
	v_add_u32_dpp v25, v25, v25 row_bcast:31 row_mask:0xc bank_mask:0xf
	s_nop 1
	v_readlane_b32 s18, v25, 63
	v_mov_b32_e32 v24, 0
	s_nop 1
	v_sub_u32_e32 v25, s18, v25
	v_add_u32_e32 v25, v25, v18
	v_sub_u32_e32 v18, v25, v18
	v_cmp_le_u32_e32 vcc, v6, v25
	v_cmp_lt_u32_e64 s[18:19], v18, v6
	s_and_b64 s[18:19], vcc, s[18:19]
	v_mov_b32_e32 v25, 0
	s_and_saveexec_b64 s[20:21], s[18:19]
	s_cbranch_execz .LBB0_475
	v_add_u32_e32 v25, v18, v3
	v_cmp_lt_u32_e32 vcc, v25, v6
	v_mov_b32_e32 v24, 3
	s_and_saveexec_b64 s[28:29], vcc
	s_cbranch_execz .LBB0_474
	v_add_u32_e32 v3, v25, v2
	v_cmp_lt_u32_e32 vcc, v3, v6
	v_mov_b32_e32 v24, 2
	s_and_saveexec_b64 s[62:63], vcc
	v_add_u32_e32 v2, v3, v1
	v_cmp_ge_u32_e32 vcc, v2, v6
	s_nop 1
	v_cndmask_b32_e32 v25, v2, v3, vcc
	v_cndmask_b32_e64 v24, 0, 1, vcc
	v_cndmask_b32_e32 v2, v0, v1, vcc
	s_or_b64 exec, exec, s[62:63]
	v_readlane_b32 s64, v251, 54
	v_mov_b32_e32 v3, v2
	v_mov_b32_e32 v18, v25
	v_readlane_b32 s65, v251, 55
